# v29 + software-pipelined norm1 for layer 0 (reads x/ctx inputs, writes f32 residual copy and h; 3 rows in flight)
# speedup vs baseline: 1.0000x; 1.0000x over previous
; __device__ __forceinline__ int opaque_tid() { int t = threadIdx.x; asm volatile("" : "+v"(t)); return t; }
; __device__ __forceinline__ unsigned pk2(float lo, float hi) { f32x2_t v = {lo, hi}; bf16x2_t b = __builtin_convertvector(v, bf16x2_t); return __builtin_bit_cast(unsigned, b); }
; __device__ __forceinline__ void phase_norm(const Params& P, int l, int which, bool first) {
;     const int tid = opaque_tid(), lane = tid & 63, wave = tid >> 6;
;     const int gw = blockIdx.x * 8 + wave, NGW = gridDim.x * 8;
;     const float* gain = (which == 0 ? P.norm1 : P.norm2) + (size_t)l * DM;
;     const float* mod = (const float*)(P.ws + WS_MOD) + (size_t)l * 17 * MODW + (which == 0 ? 0 : 3 * DM);
;     bf16_t* H = (bf16_t*)(P.ws + WS_H);
;     for (int r = gw; r < ROWS; r += NGW) {
;         const int b = r / TT, t = r - b * TT; const int bb = (t < CTX) ? 16 : b;
;         float* xr = xrow_ptr(P, r);
;         const float* src = first ? ((t < CTX) ? P.ctx + ((size_t)b * CTX + t) * DM : P.x + ((size_t)b * SEQ + (t - CTX)) * DM) : xr;
;         f32x4 v[4]; float s2 = 0.f;
; #pragma unroll
;         for (int j = 0; j < 4; ++j) { v[j] = *((const f32x4*)src + lane + 64 * j); s2 += (v[j].x * v[j].x + v[j].y * v[j].y) + (v[j].z * v[j].z + v[j].w * v[j].w); }
;         if (first) {
; #pragma unroll
;             for (int j = 0; j < 4; ++j) *((f32x4*)xr + lane + 64 * j) = v[j];
;         }
;         const float rstd = 1.0f / sqrtf(wave_sum(s2, lane) * (1.0f / DM) + RMS_EPS);
;         const float* mrow = mod + (size_t)bb * MODW;
; #pragma unroll
;         for (int j = 0; j < 4; ++j) {
;             const int c0 = 4 * (lane + 64 * j);
;             const f32x4 g = *(const f32x4*)(gain + c0), sh = *(const f32x4*)(mrow + c0), scl = *(const f32x4*)(mrow + DM + c0);
;             const f32x4 y = v[j] * rstd * g * (scl + 1.0f) + sh;
;             u32x2 w; w.x = pk2(y.x, y.y); w.y = pk2(y.z, y.w);
;             *(u32x2*)(H + (size_t)r * DM + c0) = w;
;         }
;     }
.Lnf_n1_first:
	s_load_dwordx2 s[40:41], s[38:39], 0x0
	s_load_dwordx2 s[48:49], s[38:39], 0x10
	v_readlane_b32 s8, v255, 2
	v_readlane_b32 s9, v254, 63
	v_readlane_b32 s100, v255, 0
	v_readfirstlane_b32 s101, v16
	v_and_b32_e32 v120, 63, v200
	v_lshlrev_b32_e32 v121, 3, v120
	v_lshlrev_b32_e32 v32, 2, v120
	v_xor_b32_e32 v122, 4, v32
	v_xor_b32_e32 v123, 8, v32
	v_xor_b32_e32 v124, 16, v32
	v_xor_b32_e32 v125, 32, v32
	v_xor_b32_e32 v126, 64, v32
	v_xor_b32_e32 v127, 0x80, v32
	v_lshlrev_b32_e32 v120, 4, v120
	s_waitcnt lgkmcnt(0)
	s_add_u32 s8, s58, s8
	s_addc_u32 s9, s59, s9
	s_add_u32 s50, s8, 0x101000
	s_addc_u32 s51, s9, 0
	s_lshl_b32 s100, s100, 12
	s_add_u32 s12, s44, s100
	s_addc_u32 s13, s45, 0
	s_add_u32 s36, s58, 0x4500000
	s_addc_u32 s37, s59, 0
	global_load_dwordx4 v[162:165], v120, s[12:13]
	global_load_dwordx4 v[166:169], v120, s[12:13] offset:1024
	global_load_dwordx4 v[170:173], v120, s[12:13] offset:2048
	global_load_dwordx4 v[174:177], v120, s[12:13] offset:3072
	s_lshr_b32 s8, s101, 8
	s_mul_i32 s8, s8, 57
	s_lshr_b32 s8, s8, 9
	s_mul_i32 s9, s8, 0x900
	s_sub_u32 s9, s101, s9
	s_lshl_b32 s12, s8, 11
	s_add_u32 s12, s12, s9
	s_sub_u32 s12, s12, 0x100
	s_lshl_b32 s8, s8, 8
	s_add_u32 s8, s8, s9
	s_cmp_lt_u32 s9, 0x100
	s_cselect_b32 s8, s8, s12
	s_cselect_b32 s12, s48, s40
	s_cselect_b32 s13, s49, s41
	s_lshl_b32 s8, s8, 12
	s_add_u32 s12, s12, s8
	s_addc_u32 s13, s13, 0
	global_load_dwordx4 v[0:3], v120, s[12:13]
	global_load_dwordx4 v[4:7], v120, s[12:13] offset:1024
	global_load_dwordx4 v[8:11], v120, s[12:13] offset:2048
	global_load_dwordx4 v[12:15], v120, s[12:13] offset:3072
	s_add_u32 s100, s101, s68
	s_cmp_le_u32 s100, s71
	s_cselect_b32 s100, s100, s101
	s_lshr_b32 s8, s100, 8
	s_mul_i32 s8, s8, 57
	s_lshr_b32 s8, s8, 9
	s_mul_i32 s9, s8, 0x900
	s_sub_u32 s9, s100, s9
	s_lshl_b32 s12, s8, 11
	s_add_u32 s12, s12, s9
	s_sub_u32 s12, s12, 0x100
	s_lshl_b32 s8, s8, 8
	s_add_u32 s8, s8, s9
	s_cmp_lt_u32 s9, 0x100
	s_cselect_b32 s8, s8, s12
	s_cselect_b32 s12, s48, s40
	s_cselect_b32 s13, s49, s41
	s_lshl_b32 s8, s8, 12
	s_add_u32 s12, s12, s8
	s_addc_u32 s13, s13, 0
	global_load_dwordx4 v[16:19], v120, s[12:13]
	global_load_dwordx4 v[20:23], v120, s[12:13] offset:1024
	global_load_dwordx4 v[24:27], v120, s[12:13] offset:2048
	global_load_dwordx4 v[28:31], v120, s[12:13] offset:3072
	s_mul_i32 s100, s68, 2
	s_add_u32 s100, s100, s101
	s_cmp_le_u32 s100, s71
	s_cselect_b32 s100, s100, s101
	s_lshr_b32 s8, s100, 8
	s_mul_i32 s8, s8, 57
	s_lshr_b32 s8, s8, 9
	s_mul_i32 s9, s8, 0x900
	s_sub_u32 s9, s100, s9
	s_lshl_b32 s12, s8, 11
	s_add_u32 s12, s12, s9
	s_sub_u32 s12, s12, 0x100
	s_lshl_b32 s8, s8, 8
	s_add_u32 s8, s8, s9
	s_cmp_lt_u32 s9, 0x100
	s_cselect_b32 s8, s8, s12
	s_cselect_b32 s12, s48, s40
	s_cselect_b32 s13, s49, s41
	s_lshl_b32 s8, s8, 12
	s_add_u32 s12, s12, s8
	s_addc_u32 s13, s13, 0
	global_load_dwordx4 v[40:43], v120, s[12:13]
	global_load_dwordx4 v[44:47], v120, s[12:13] offset:1024
	global_load_dwordx4 v[48:51], v120, s[12:13] offset:2048
	global_load_dwordx4 v[52:55], v120, s[12:13] offset:3072
	s_lshr_b32 s8, s101, 8
	s_mul_i32 s8, s8, 57
	s_lshr_b32 s8, s8, 9
	s_mul_i32 s9, s8, 0x900
	s_sub_u32 s9, s101, s9
	s_cmp_lt_u32 s9, 0x100
	s_cselect_b32 s8, 16, s8
	s_mul_i32 s8, s8, 0x6000
	s_add_u32 s12, s50, s8
	s_addc_u32 s13, s51, 0
	global_load_dwordx4 v[56:59], v120, s[12:13] offset:-4096
	global_load_dwordx4 v[60:63], v120, s[12:13] offset:-3072
	global_load_dwordx4 v[64:67], v120, s[12:13] offset:-2048
	global_load_dwordx4 v[68:71], v120, s[12:13] offset:-1024
	global_load_dwordx4 v[72:75], v120, s[12:13]
	global_load_dwordx4 v[76:79], v120, s[12:13] offset:1024
	global_load_dwordx4 v[80:83], v120, s[12:13] offset:2048
	global_load_dwordx4 v[84:87], v120, s[12:13] offset:3072
	s_waitcnt vmcnt(16)
	s_add_u32 s100, s101, s68
	s_cmp_le_u32 s100, s71
	s_cselect_b32 s100, s100, s101
	s_lshr_b32 s8, s100, 8
	s_mul_i32 s8, s8, 57
	s_lshr_b32 s8, s8, 9
	s_mul_i32 s9, s8, 0x900
	s_sub_u32 s9, s100, s9
	s_cmp_lt_u32 s9, 0x100
	s_cselect_b32 s8, 16, s8
	s_mul_i32 s8, s8, 0x6000
	s_add_u32 s12, s50, s8
	s_addc_u32 s13, s51, 0
	global_load_dwordx4 v[88:91], v120, s[12:13] offset:-4096
	global_load_dwordx4 v[92:95], v120, s[12:13] offset:-3072
	global_load_dwordx4 v[96:99], v120, s[12:13] offset:-2048
	global_load_dwordx4 v[100:103], v120, s[12:13] offset:-1024
	global_load_dwordx4 v[104:107], v120, s[12:13]
	global_load_dwordx4 v[108:111], v120, s[12:13] offset:1024
	global_load_dwordx4 v[112:115], v120, s[12:13] offset:2048
	global_load_dwordx4 v[116:119], v120, s[12:13] offset:3072
	v_mul_f32_e32 v32, v1, v1
	v_mul_f32_e32 v33, v3, v3
	v_fmac_f32_e32 v32, v0, v0
	v_fmac_f32_e32 v33, v2, v2
	v_add_f32_e32 v34, v32, v33
	v_mul_f32_e32 v32, v5, v5
	v_mul_f32_e32 v33, v7, v7
	v_fmac_f32_e32 v32, v4, v4
	v_fmac_f32_e32 v33, v6, v6
	v_add_f32_e32 v32, v32, v33
	v_add_f32_e32 v34, v34, v32
	v_mul_f32_e32 v32, v9, v9
	v_mul_f32_e32 v33, v11, v11
	v_fmac_f32_e32 v32, v8, v8
	v_fmac_f32_e32 v33, v10, v10
	v_add_f32_e32 v32, v32, v33
	v_add_f32_e32 v34, v34, v32
	v_mul_f32_e32 v32, v13, v13
	v_mul_f32_e32 v33, v15, v15
	v_fmac_f32_e32 v32, v12, v12
	v_fmac_f32_e32 v33, v14, v14
	v_add_f32_e32 v32, v32, v33
	v_add_f32_e32 v34, v34, v32
	ds_bpermute_b32 v32, v122, v34
	s_waitcnt lgkmcnt(0)
	v_add_f32_e32 v34, v34, v32
	ds_bpermute_b32 v32, v123, v34
	s_waitcnt lgkmcnt(0)
	v_add_f32_e32 v34, v34, v32
	ds_bpermute_b32 v32, v124, v34
	s_waitcnt lgkmcnt(0)
	v_add_f32_e32 v34, v34, v32
	ds_bpermute_b32 v32, v125, v34
	s_waitcnt lgkmcnt(0)
	v_add_f32_e32 v34, v34, v32
	ds_bpermute_b32 v32, v126, v34
	s_waitcnt lgkmcnt(0)
; __device__ __forceinline__ unsigned pk2(float lo, float hi) { f32x2_t v = {lo, hi}; bf16x2_t b = __builtin_convertvector(v, bf16x2_t); return __builtin_bit_cast(unsigned, b); }
; __device__ __forceinline__ void phase_norm(const Params& P, int l, int which, bool first) {
;     ...
;     for (int r = gw; r < ROWS; r += NGW) {
;         const int b = r / TT, t = r - b * TT; const int bb = (t < CTX) ? 16 : b;
;         float* xr = xrow_ptr(P, r);
;         const float* src = first ? ((t < CTX) ? P.ctx + ((size_t)b * CTX + t) * DM : P.x + ((size_t)b * SEQ + (t - CTX)) * DM) : xr;
;         f32x4 v[4]; float s2 = 0.f;
; #pragma unroll
;         for (int j = 0; j < 4; ++j) { v[j] = *((const f32x4*)src + lane + 64 * j); s2 += (v[j].x * v[j].x + v[j].y * v[j].y) + (v[j].z * v[j].z + v[j].w * v[j].w); }
;         if (first) {
; #pragma unroll
;             for (int j = 0; j < 4; ++j) *((f32x4*)xr + lane + 64 * j) = v[j];
;         }
;         const float rstd = 1.0f / sqrtf(wave_sum(s2, lane) * (1.0f / DM) + RMS_EPS);
;         const float* mrow = mod + (size_t)bb * MODW;
; #pragma unroll
;         for (int j = 0; j < 4; ++j) {
;             const int c0 = 4 * (lane + 64 * j);
;             const f32x4 g = *(const f32x4*)(gain + c0), sh = *(const f32x4*)(mrow + c0), scl = *(const f32x4*)(mrow + DM + c0);
;             const f32x4 y = v[j] * rstd * g * (scl + 1.0f) + sh;
;             u32x2 w; w.x = pk2(y.x, y.y); w.y = pk2(y.z, y.w);
;             *(u32x2*)(H + (size_t)r * DM + c0) = w;
;         }
;     }
	v_add_f32_e32 v34, v34, v32
	ds_bpermute_b32 v32, v127, v34
	s_waitcnt lgkmcnt(0)
	v_add_f32_e32 v34, v34, v32
	v_fmamk_f32 v34, v34, 0x3a800000, v201
	v_cmp_gt_f32_e32 vcc, 0xf800000, v34
	v_mul_f32_e32 v32, 0x4f800000, v34
	s_nop 0
	v_cndmask_b32_e32 v34, v34, v32, vcc
	v_sqrt_f32_e32 v32, v34
	s_nop 0
	v_add_u32_e32 v35, -1, v32
	v_fma_f32 v36, -v35, v32, v34
	v_cmp_ge_f32_e64 s[38:39], 0, v36
	v_add_u32_e32 v36, 1, v32
	s_nop 0
	v_cndmask_b32_e64 v35, v32, v35, s[38:39]
	v_fma_f32 v32, -v36, v32, v34
	v_cmp_lt_f32_e64 s[38:39], 0, v32
	s_nop 1
	v_cndmask_b32_e64 v32, v35, v36, s[38:39]
	v_mul_f32_e32 v35, 0x37800000, v32
	v_cndmask_b32_e32 v32, v32, v35, vcc
	v_cmp_class_f32_e32 vcc, v34, v202
	s_nop 1
	v_cndmask_b32_e32 v34, v32, v34, vcc
	v_div_scale_f32 v32, s[38:39], v34, v34, 1.0
	v_rcp_f32_e32 v35, v32
	s_nop 0
	v_fma_f32 v36, -v32, v35, 1.0
	v_fmac_f32_e32 v35, v36, v35
	v_div_scale_f32 v36, vcc, 1.0, v34, 1.0
	v_mul_f32_e32 v37, v36, v35
	v_fma_f32 v178, -v32, v37, v36
	v_fmac_f32_e32 v37, v178, v35
	v_fma_f32 v32, -v32, v37, v36
	v_div_fmas_f32 v32, v32, v35, v37
	v_div_fixup_f32 v179, v32, v34, 1.0
	s_lshl_b32 s8, s101, 11
	s_add_u32 s12, s58, s8
	s_addc_u32 s13, s59, 0
	s_add_u32 s12, s12, 0x5500000
	s_addc_u32 s13, s13, 0
	s_waitcnt vmcnt(8)
	v_mul_f32_e32 v193, v0, v179
	v_add_f32_e32 v192, 1.0, v72
	v_mul_f32_e32 v193, v162, v193
	v_fma_f32 v180, v192, v193, v56
	v_mul_f32_e32 v193, v1, v179
	v_add_f32_e32 v192, 1.0, v73
	v_mul_f32_e32 v193, v163, v193
	v_fma_f32 v181, v192, v193, v57
	v_mul_f32_e32 v193, v2, v179
	v_add_f32_e32 v192, 1.0, v74
	v_mul_f32_e32 v193, v164, v193
	v_fma_f32 v182, v192, v193, v58
	v_mul_f32_e32 v193, v3, v179
	v_add_f32_e32 v192, 1.0, v75
	v_mul_f32_e32 v193, v165, v193
	v_fma_f32 v183, v192, v193, v59
	v_cvt_pk_bf16_f32 v184, v180, v181
	v_cvt_pk_bf16_f32 v185, v182, v183
	global_store_dwordx2 v121, v[184:185], s[12:13]
	v_mul_f32_e32 v193, v4, v179
	v_add_f32_e32 v192, 1.0, v76
	v_mul_f32_e32 v193, v166, v193
	v_fma_f32 v180, v192, v193, v60
	v_mul_f32_e32 v193, v5, v179
	v_add_f32_e32 v192, 1.0, v77
	v_mul_f32_e32 v193, v167, v193
	v_fma_f32 v181, v192, v193, v61
	v_mul_f32_e32 v193, v6, v179
	v_add_f32_e32 v192, 1.0, v78
	v_mul_f32_e32 v193, v168, v193
	v_fma_f32 v182, v192, v193, v62
	v_mul_f32_e32 v193, v7, v179
	v_add_f32_e32 v192, 1.0, v79
	v_mul_f32_e32 v193, v169, v193
	v_fma_f32 v183, v192, v193, v63
	v_cvt_pk_bf16_f32 v186, v180, v181
	v_cvt_pk_bf16_f32 v187, v182, v183
	global_store_dwordx2 v121, v[186:187], s[12:13] offset:512
	v_mul_f32_e32 v193, v8, v179
	v_add_f32_e32 v192, 1.0, v80
	v_mul_f32_e32 v193, v170, v193
	v_fma_f32 v180, v192, v193, v64
	v_mul_f32_e32 v193, v9, v179
	v_add_f32_e32 v192, 1.0, v81
	v_mul_f32_e32 v193, v171, v193
	v_fma_f32 v181, v192, v193, v65
	v_mul_f32_e32 v193, v10, v179
	v_add_f32_e32 v192, 1.0, v82
	v_mul_f32_e32 v193, v172, v193
	v_fma_f32 v182, v192, v193, v66
	v_mul_f32_e32 v193, v11, v179
	v_add_f32_e32 v192, 1.0, v83
	v_mul_f32_e32 v193, v173, v193
	v_fma_f32 v183, v192, v193, v67
	v_cvt_pk_bf16_f32 v188, v180, v181
	v_cvt_pk_bf16_f32 v189, v182, v183
	global_store_dwordx2 v121, v[188:189], s[12:13] offset:1024
	v_mul_f32_e32 v193, v12, v179
	v_add_f32_e32 v192, 1.0, v84
	v_mul_f32_e32 v193, v174, v193
	v_fma_f32 v180, v192, v193, v68
	v_mul_f32_e32 v193, v13, v179
	v_add_f32_e32 v192, 1.0, v85
	v_mul_f32_e32 v193, v175, v193
	v_fma_f32 v181, v192, v193, v69
	v_mul_f32_e32 v193, v14, v179
	v_add_f32_e32 v192, 1.0, v86
	v_mul_f32_e32 v193, v176, v193
	v_fma_f32 v182, v192, v193, v70
	v_mul_f32_e32 v193, v15, v179
	v_add_f32_e32 v192, 1.0, v87
	v_mul_f32_e32 v193, v177, v193
	v_fma_f32 v183, v192, v193, v71
	v_cvt_pk_bf16_f32 v190, v180, v181
	v_cvt_pk_bf16_f32 v191, v182, v183
	global_store_dwordx2 v121, v[190:191], s[12:13] offset:1536
	s_lshr_b32 s8, s101, 8
	s_mul_i32 s8, s8, 57
	s_lshr_b32 s8, s8, 9
	s_mul_i32 s9, s8, 0x900
	s_sub_u32 s9, s101, s9
	s_lshl_b32 s12, s8, 11
	s_add_u32 s12, s12, s9
	s_sub_u32 s12, s12, 0x100
	s_lshl_b32 s8, s8, 8
	s_add_u32 s8, s8, s9
	s_cmp_lt_u32 s9, 0x100
	s_cselect_b32 s8, s8, s12
	s_cselect_b32 s12, s36, s56
	s_cselect_b32 s13, s37, s57
	s_lshl_b32 s8, s8, 12
	s_add_u32 s12, s12, s8
	s_addc_u32 s13, s13, 0
	global_store_dwordx4 v120, v[0:3], s[12:13]
	global_store_dwordx4 v120, v[4:7], s[12:13] offset:1024
	global_store_dwordx4 v120, v[8:11], s[12:13] offset:2048
	global_store_dwordx4 v120, v[12:15], s[12:13] offset:3072
	s_mul_i32 s100, s68, 3
	s_add_u32 s100, s100, s101
	s_cmp_le_u32 s100, s71
	s_cselect_b32 s100, s100, s101
	s_lshr_b32 s8, s100, 8
	s_mul_i32 s8, s8, 57
	s_lshr_b32 s8, s8, 9
	s_mul_i32 s9, s8, 0x900
	s_sub_u32 s9, s100, s9
	s_lshl_b32 s12, s8, 11
	s_add_u32 s12, s12, s9
	s_sub_u32 s12, s12, 0x100
	s_lshl_b32 s8, s8, 8
	s_add_u32 s8, s8, s9
	s_cmp_lt_u32 s9, 0x100
	s_cselect_b32 s8, s8, s12
	s_cselect_b32 s12, s48, s40
	s_cselect_b32 s13, s49, s41
	s_lshl_b32 s8, s8, 12
	s_add_u32 s12, s12, s8
	s_addc_u32 s13, s13, 0
	global_load_dwordx4 v[0:3], v120, s[12:13]
	global_load_dwordx4 v[4:7], v120, s[12:13] offset:1024
	global_load_dwordx4 v[8:11], v120, s[12:13] offset:2048
	global_load_dwordx4 v[12:15], v120, s[12:13] offset:3072
	s_add_u32 s101, s101, s68
	s_cmp_gt_u32 s101, s71
	s_cbranch_scc1 .Lnf_n1f_exit
; __device__ __forceinline__ unsigned pk2(float lo, float hi) { f32x2_t v = {lo, hi}; bf16x2_t b = __builtin_convertvector(v, bf16x2_t); return __builtin_bit_cast(unsigned, b); }
; __device__ __forceinline__ void phase_norm(const Params& P, int l, int which, bool first) {
;     ...
;     for (int r = gw; r < ROWS; r += NGW) {
;         const int b = r / TT, t = r - b * TT; const int bb = (t < CTX) ? 16 : b;
;         float* xr = xrow_ptr(P, r);
;         const float* src = first ? ((t < CTX) ? P.ctx + ((size_t)b * CTX + t) * DM : P.x + ((size_t)b * SEQ + (t - CTX)) * DM) : xr;
;         f32x4 v[4]; float s2 = 0.f;
; #pragma unroll
;         for (int j = 0; j < 4; ++j) { v[j] = *((const f32x4*)src + lane + 64 * j); s2 += (v[j].x * v[j].x + v[j].y * v[j].y) + (v[j].z * v[j].z + v[j].w * v[j].w); }
;         if (first) {
; #pragma unroll
;             for (int j = 0; j < 4; ++j) *((f32x4*)xr + lane + 64 * j) = v[j];
;         }
;         const float rstd = 1.0f / sqrtf(wave_sum(s2, lane) * (1.0f / DM) + RMS_EPS);
;         const float* mrow = mod + (size_t)bb * MODW;
; #pragma unroll
;         for (int j = 0; j < 4; ++j) {
;             const int c0 = 4 * (lane + 64 * j);
;             const f32x4 g = *(const f32x4*)(gain + c0), sh = *(const f32x4*)(mrow + c0), scl = *(const f32x4*)(mrow + DM + c0);
;             const f32x4 y = v[j] * rstd * g * (scl + 1.0f) + sh;
;             u32x2 w; w.x = pk2(y.x, y.y); w.y = pk2(y.z, y.w);
;             *(u32x2*)(H + (size_t)r * DM + c0) = w;
;         }
;     }
	s_waitcnt vmcnt(32)
	s_add_u32 s100, s101, s68
	s_cmp_le_u32 s100, s71
	s_cselect_b32 s100, s100, s101
	s_lshr_b32 s8, s100, 8
	s_mul_i32 s8, s8, 57
	s_lshr_b32 s8, s8, 9
	s_mul_i32 s9, s8, 0x900
	s_sub_u32 s9, s100, s9
	s_cmp_lt_u32 s9, 0x100
	s_cselect_b32 s8, 16, s8
	s_mul_i32 s8, s8, 0x6000
	s_add_u32 s12, s50, s8
	s_addc_u32 s13, s51, 0
	global_load_dwordx4 v[130:133], v120, s[12:13] offset:-4096
	global_load_dwordx4 v[134:137], v120, s[12:13] offset:-3072
	global_load_dwordx4 v[138:141], v120, s[12:13] offset:-2048
	global_load_dwordx4 v[142:145], v120, s[12:13] offset:-1024
	global_load_dwordx4 v[146:149], v120, s[12:13]
	global_load_dwordx4 v[150:153], v120, s[12:13] offset:1024
	global_load_dwordx4 v[154:157], v120, s[12:13] offset:2048
	global_load_dwordx4 v[158:161], v120, s[12:13] offset:3072
	v_mul_f32_e32 v32, v17, v17
	v_mul_f32_e32 v33, v19, v19
	v_fmac_f32_e32 v32, v16, v16
	v_fmac_f32_e32 v33, v18, v18
	v_add_f32_e32 v34, v32, v33
	v_mul_f32_e32 v32, v21, v21
	v_mul_f32_e32 v33, v23, v23
	v_fmac_f32_e32 v32, v20, v20
	v_fmac_f32_e32 v33, v22, v22
	v_add_f32_e32 v32, v32, v33
	v_add_f32_e32 v34, v34, v32
	v_mul_f32_e32 v32, v25, v25
	v_mul_f32_e32 v33, v27, v27
	v_fmac_f32_e32 v32, v24, v24
	v_fmac_f32_e32 v33, v26, v26
	v_add_f32_e32 v32, v32, v33
	v_add_f32_e32 v34, v34, v32
	v_mul_f32_e32 v32, v29, v29
	v_mul_f32_e32 v33, v31, v31
	v_fmac_f32_e32 v32, v28, v28
	v_fmac_f32_e32 v33, v30, v30
	v_add_f32_e32 v32, v32, v33
	v_add_f32_e32 v34, v34, v32
	ds_bpermute_b32 v32, v122, v34
	s_waitcnt lgkmcnt(0)
	v_add_f32_e32 v34, v34, v32
	ds_bpermute_b32 v32, v123, v34
	s_waitcnt lgkmcnt(0)
	v_add_f32_e32 v34, v34, v32
	ds_bpermute_b32 v32, v124, v34
	s_waitcnt lgkmcnt(0)
	v_add_f32_e32 v34, v34, v32
	ds_bpermute_b32 v32, v125, v34
	s_waitcnt lgkmcnt(0)
	v_add_f32_e32 v34, v34, v32
	ds_bpermute_b32 v32, v126, v34
	s_waitcnt lgkmcnt(0)
	v_add_f32_e32 v34, v34, v32
	ds_bpermute_b32 v32, v127, v34
	s_waitcnt lgkmcnt(0)
	v_add_f32_e32 v34, v34, v32
	v_fmamk_f32 v34, v34, 0x3a800000, v201
	v_cmp_gt_f32_e32 vcc, 0xf800000, v34
	v_mul_f32_e32 v32, 0x4f800000, v34
	s_nop 0
	v_cndmask_b32_e32 v34, v34, v32, vcc
	v_sqrt_f32_e32 v32, v34
	s_nop 0
	v_add_u32_e32 v35, -1, v32
	v_fma_f32 v36, -v35, v32, v34
	v_cmp_ge_f32_e64 s[38:39], 0, v36
	v_add_u32_e32 v36, 1, v32
	s_nop 0
	v_cndmask_b32_e64 v35, v32, v35, s[38:39]
	v_fma_f32 v32, -v36, v32, v34
	v_cmp_lt_f32_e64 s[38:39], 0, v32
	s_nop 1
	v_cndmask_b32_e64 v32, v35, v36, s[38:39]
	v_mul_f32_e32 v35, 0x37800000, v32
	v_cndmask_b32_e32 v32, v32, v35, vcc
	v_cmp_class_f32_e32 vcc, v34, v202
	s_nop 1
	v_cndmask_b32_e32 v34, v32, v34, vcc
	v_div_scale_f32 v32, s[38:39], v34, v34, 1.0
	v_rcp_f32_e32 v35, v32
	s_nop 0
	v_fma_f32 v36, -v32, v35, 1.0
	v_fmac_f32_e32 v35, v36, v35
	v_div_scale_f32 v36, vcc, 1.0, v34, 1.0
	v_mul_f32_e32 v37, v36, v35
	v_fma_f32 v178, -v32, v37, v36
	v_fmac_f32_e32 v37, v178, v35
	v_fma_f32 v32, -v32, v37, v36
	v_div_fmas_f32 v32, v32, v35, v37
	v_div_fixup_f32 v179, v32, v34, 1.0
	s_lshl_b32 s8, s101, 11
	s_add_u32 s12, s58, s8
	s_addc_u32 s13, s59, 0
	s_add_u32 s12, s12, 0x5500000
	s_addc_u32 s13, s13, 0
	s_waitcnt vmcnt(20)
	v_mul_f32_e32 v193, v16, v179
	v_add_f32_e32 v192, 1.0, v104
	v_mul_f32_e32 v193, v162, v193
	v_fma_f32 v180, v192, v193, v88
	v_mul_f32_e32 v193, v17, v179
	v_add_f32_e32 v192, 1.0, v105
	v_mul_f32_e32 v193, v163, v193
	v_fma_f32 v181, v192, v193, v89
	v_mul_f32_e32 v193, v18, v179
	v_add_f32_e32 v192, 1.0, v106
	v_mul_f32_e32 v193, v164, v193
	v_fma_f32 v182, v192, v193, v90
	v_mul_f32_e32 v193, v19, v179
	v_add_f32_e32 v192, 1.0, v107
	v_mul_f32_e32 v193, v165, v193
	v_fma_f32 v183, v192, v193, v91
	v_cvt_pk_bf16_f32 v184, v180, v181
	v_cvt_pk_bf16_f32 v185, v182, v183
	global_store_dwordx2 v121, v[184:185], s[12:13]
	v_mul_f32_e32 v193, v20, v179
	v_add_f32_e32 v192, 1.0, v108
	v_mul_f32_e32 v193, v166, v193
	v_fma_f32 v180, v192, v193, v92
	v_mul_f32_e32 v193, v21, v179
	v_add_f32_e32 v192, 1.0, v109
	v_mul_f32_e32 v193, v167, v193
	v_fma_f32 v181, v192, v193, v93
	v_mul_f32_e32 v193, v22, v179
	v_add_f32_e32 v192, 1.0, v110
	v_mul_f32_e32 v193, v168, v193
	v_fma_f32 v182, v192, v193, v94
	v_mul_f32_e32 v193, v23, v179
	v_add_f32_e32 v192, 1.0, v111
	v_mul_f32_e32 v193, v169, v193
	v_fma_f32 v183, v192, v193, v95
	v_cvt_pk_bf16_f32 v186, v180, v181
	v_cvt_pk_bf16_f32 v187, v182, v183
	global_store_dwordx2 v121, v[186:187], s[12:13] offset:512
	v_mul_f32_e32 v193, v24, v179
	v_add_f32_e32 v192, 1.0, v112
	v_mul_f32_e32 v193, v170, v193
	v_fma_f32 v180, v192, v193, v96
	v_mul_f32_e32 v193, v25, v179
	v_add_f32_e32 v192, 1.0, v113
	v_mul_f32_e32 v193, v171, v193
	v_fma_f32 v181, v192, v193, v97
	v_mul_f32_e32 v193, v26, v179
	v_add_f32_e32 v192, 1.0, v114
	v_mul_f32_e32 v193, v172, v193
	v_fma_f32 v182, v192, v193, v98
	v_mul_f32_e32 v193, v27, v179
	v_add_f32_e32 v192, 1.0, v115
	v_mul_f32_e32 v193, v173, v193
	v_fma_f32 v183, v192, v193, v99
	v_cvt_pk_bf16_f32 v188, v180, v181
	v_cvt_pk_bf16_f32 v189, v182, v183
	global_store_dwordx2 v121, v[188:189], s[12:13] offset:1024
	v_mul_f32_e32 v193, v28, v179
	v_add_f32_e32 v192, 1.0, v116
	v_mul_f32_e32 v193, v174, v193
	v_fma_f32 v180, v192, v193, v100
	v_mul_f32_e32 v193, v29, v179
	v_add_f32_e32 v192, 1.0, v117
	v_mul_f32_e32 v193, v175, v193
	v_fma_f32 v181, v192, v193, v101
	v_mul_f32_e32 v193, v30, v179
	v_add_f32_e32 v192, 1.0, v118
	v_mul_f32_e32 v193, v176, v193
	v_fma_f32 v182, v192, v193, v102
	v_mul_f32_e32 v193, v31, v179
	v_add_f32_e32 v192, 1.0, v119
	v_mul_f32_e32 v193, v177, v193
	v_fma_f32 v183, v192, v193, v103
	v_cvt_pk_bf16_f32 v190, v180, v181
	v_cvt_pk_bf16_f32 v191, v182, v183
; __device__ __forceinline__ unsigned pk2(float lo, float hi) { f32x2_t v = {lo, hi}; bf16x2_t b = __builtin_convertvector(v, bf16x2_t); return __builtin_bit_cast(unsigned, b); }
; __device__ __forceinline__ void phase_norm(const Params& P, int l, int which, bool first) {
;     ...
;     for (int r = gw; r < ROWS; r += NGW) {
;         const int b = r / TT, t = r - b * TT; const int bb = (t < CTX) ? 16 : b;
;         float* xr = xrow_ptr(P, r);
;         const float* src = first ? ((t < CTX) ? P.ctx + ((size_t)b * CTX + t) * DM : P.x + ((size_t)b * SEQ + (t - CTX)) * DM) : xr;
;         f32x4 v[4]; float s2 = 0.f;
; #pragma unroll
;         for (int j = 0; j < 4; ++j) { v[j] = *((const f32x4*)src + lane + 64 * j); s2 += (v[j].x * v[j].x + v[j].y * v[j].y) + (v[j].z * v[j].z + v[j].w * v[j].w); }
;         if (first) {
; #pragma unroll
;             for (int j = 0; j < 4; ++j) *((f32x4*)xr + lane + 64 * j) = v[j];
;         }
;         const float rstd = 1.0f / sqrtf(wave_sum(s2, lane) * (1.0f / DM) + RMS_EPS);
;         const float* mrow = mod + (size_t)bb * MODW;
; #pragma unroll
;         for (int j = 0; j < 4; ++j) {
;             const int c0 = 4 * (lane + 64 * j);
;             const f32x4 g = *(const f32x4*)(gain + c0), sh = *(const f32x4*)(mrow + c0), scl = *(const f32x4*)(mrow + DM + c0);
;             const f32x4 y = v[j] * rstd * g * (scl + 1.0f) + sh;
;             u32x2 w; w.x = pk2(y.x, y.y); w.y = pk2(y.z, y.w);
;             *(u32x2*)(H + (size_t)r * DM + c0) = w;
;         }
;     }
	global_store_dwordx2 v121, v[190:191], s[12:13] offset:1536
	s_lshr_b32 s8, s101, 8
	s_mul_i32 s8, s8, 57
	s_lshr_b32 s8, s8, 9
	s_mul_i32 s9, s8, 0x900
	s_sub_u32 s9, s101, s9
	s_lshl_b32 s12, s8, 11
	s_add_u32 s12, s12, s9
	s_sub_u32 s12, s12, 0x100
	s_lshl_b32 s8, s8, 8
	s_add_u32 s8, s8, s9
	s_cmp_lt_u32 s9, 0x100
	s_cselect_b32 s8, s8, s12
	s_cselect_b32 s12, s36, s56
	s_cselect_b32 s13, s37, s57
	s_lshl_b32 s8, s8, 12
	s_add_u32 s12, s12, s8
	s_addc_u32 s13, s13, 0
	global_store_dwordx4 v120, v[16:19], s[12:13]
	global_store_dwordx4 v120, v[20:23], s[12:13] offset:1024
	global_store_dwordx4 v120, v[24:27], s[12:13] offset:2048
	global_store_dwordx4 v120, v[28:31], s[12:13] offset:3072
	s_mul_i32 s100, s68, 3
	s_add_u32 s100, s100, s101
	s_cmp_le_u32 s100, s71
	s_cselect_b32 s100, s100, s101
	s_lshr_b32 s8, s100, 8
	s_mul_i32 s8, s8, 57
	s_lshr_b32 s8, s8, 9
	s_mul_i32 s9, s8, 0x900
	s_sub_u32 s9, s100, s9
	s_lshl_b32 s12, s8, 11
	s_add_u32 s12, s12, s9
	s_sub_u32 s12, s12, 0x100
	s_lshl_b32 s8, s8, 8
	s_add_u32 s8, s8, s9
	s_cmp_lt_u32 s9, 0x100
	s_cselect_b32 s8, s8, s12
	s_cselect_b32 s12, s48, s40
	s_cselect_b32 s13, s49, s41
	s_lshl_b32 s8, s8, 12
	s_add_u32 s12, s12, s8
	s_addc_u32 s13, s13, 0
	global_load_dwordx4 v[16:19], v120, s[12:13]
	global_load_dwordx4 v[20:23], v120, s[12:13] offset:1024
	global_load_dwordx4 v[24:27], v120, s[12:13] offset:2048
	global_load_dwordx4 v[28:31], v120, s[12:13] offset:3072
	s_add_u32 s101, s101, s68
	s_cmp_gt_u32 s101, s71
	s_cbranch_scc1 .Lnf_n1f_exit
	s_waitcnt vmcnt(40)
	s_add_u32 s100, s101, s68
	s_cmp_le_u32 s100, s71
	s_cselect_b32 s100, s100, s101
	s_lshr_b32 s8, s100, 8
	s_mul_i32 s8, s8, 57
	s_lshr_b32 s8, s8, 9
	s_mul_i32 s9, s8, 0x900
	s_sub_u32 s9, s100, s9
	s_cmp_lt_u32 s9, 0x100
	s_cselect_b32 s8, 16, s8
	s_mul_i32 s8, s8, 0x6000
	s_add_u32 s12, s50, s8
	s_addc_u32 s13, s51, 0
	global_load_dwordx4 v[56:59], v120, s[12:13] offset:-4096
	global_load_dwordx4 v[60:63], v120, s[12:13] offset:-3072
	global_load_dwordx4 v[64:67], v120, s[12:13] offset:-2048
	global_load_dwordx4 v[68:71], v120, s[12:13] offset:-1024
	global_load_dwordx4 v[72:75], v120, s[12:13]
	global_load_dwordx4 v[76:79], v120, s[12:13] offset:1024
	global_load_dwordx4 v[80:83], v120, s[12:13] offset:2048
	global_load_dwordx4 v[84:87], v120, s[12:13] offset:3072
	v_mul_f32_e32 v32, v41, v41
	v_mul_f32_e32 v33, v43, v43
	v_fmac_f32_e32 v32, v40, v40
	v_fmac_f32_e32 v33, v42, v42
	v_add_f32_e32 v34, v32, v33
	v_mul_f32_e32 v32, v45, v45
	v_mul_f32_e32 v33, v47, v47
	v_fmac_f32_e32 v32, v44, v44
	v_fmac_f32_e32 v33, v46, v46
	v_add_f32_e32 v32, v32, v33
	v_add_f32_e32 v34, v34, v32
	v_mul_f32_e32 v32, v49, v49
	v_mul_f32_e32 v33, v51, v51
	v_fmac_f32_e32 v32, v48, v48
	v_fmac_f32_e32 v33, v50, v50
	v_add_f32_e32 v32, v32, v33
	v_add_f32_e32 v34, v34, v32
	v_mul_f32_e32 v32, v53, v53
	v_mul_f32_e32 v33, v55, v55
	v_fmac_f32_e32 v32, v52, v52
	v_fmac_f32_e32 v33, v54, v54
	v_add_f32_e32 v32, v32, v33
	v_add_f32_e32 v34, v34, v32
	ds_bpermute_b32 v32, v122, v34
	s_waitcnt lgkmcnt(0)
	v_add_f32_e32 v34, v34, v32
	ds_bpermute_b32 v32, v123, v34
	s_waitcnt lgkmcnt(0)
	v_add_f32_e32 v34, v34, v32
	ds_bpermute_b32 v32, v124, v34
	s_waitcnt lgkmcnt(0)
	v_add_f32_e32 v34, v34, v32
	ds_bpermute_b32 v32, v125, v34
	s_waitcnt lgkmcnt(0)
	v_add_f32_e32 v34, v34, v32
	ds_bpermute_b32 v32, v126, v34
	s_waitcnt lgkmcnt(0)
	v_add_f32_e32 v34, v34, v32
	ds_bpermute_b32 v32, v127, v34
	s_waitcnt lgkmcnt(0)
	v_add_f32_e32 v34, v34, v32
	v_fmamk_f32 v34, v34, 0x3a800000, v201
	v_cmp_gt_f32_e32 vcc, 0xf800000, v34
	v_mul_f32_e32 v32, 0x4f800000, v34
	s_nop 0
	v_cndmask_b32_e32 v34, v34, v32, vcc
	v_sqrt_f32_e32 v32, v34
	s_nop 0
	v_add_u32_e32 v35, -1, v32
	v_fma_f32 v36, -v35, v32, v34
	v_cmp_ge_f32_e64 s[38:39], 0, v36
	v_add_u32_e32 v36, 1, v32
	s_nop 0
	v_cndmask_b32_e64 v35, v32, v35, s[38:39]
	v_fma_f32 v32, -v36, v32, v34
	v_cmp_lt_f32_e64 s[38:39], 0, v32
	s_nop 1
	v_cndmask_b32_e64 v32, v35, v36, s[38:39]
	v_mul_f32_e32 v35, 0x37800000, v32
	v_cndmask_b32_e32 v32, v32, v35, vcc
	v_cmp_class_f32_e32 vcc, v34, v202
	s_nop 1
	v_cndmask_b32_e32 v34, v32, v34, vcc
	v_div_scale_f32 v32, s[38:39], v34, v34, 1.0
	v_rcp_f32_e32 v35, v32
	s_nop 0
	v_fma_f32 v36, -v32, v35, 1.0
	v_fmac_f32_e32 v35, v36, v35
	v_div_scale_f32 v36, vcc, 1.0, v34, 1.0
	v_mul_f32_e32 v37, v36, v35
	v_fma_f32 v178, -v32, v37, v36
	v_fmac_f32_e32 v37, v178, v35
	v_fma_f32 v32, -v32, v37, v36
	v_div_fmas_f32 v32, v32, v35, v37
	v_div_fixup_f32 v179, v32, v34, 1.0
	s_lshl_b32 s8, s101, 11
	s_add_u32 s12, s58, s8
	s_addc_u32 s13, s59, 0
	s_add_u32 s12, s12, 0x5500000
	s_addc_u32 s13, s13, 0
	s_waitcnt vmcnt(20)
; __device__ __forceinline__ unsigned pk2(float lo, float hi) { f32x2_t v = {lo, hi}; bf16x2_t b = __builtin_convertvector(v, bf16x2_t); return __builtin_bit_cast(unsigned, b); }
; __device__ __forceinline__ void phase_norm(const Params& P, int l, int which, bool first) {
;     ...
;     for (int r = gw; r < ROWS; r += NGW) {
;         const int b = r / TT, t = r - b * TT; const int bb = (t < CTX) ? 16 : b;
;         float* xr = xrow_ptr(P, r);
;         const float* src = first ? ((t < CTX) ? P.ctx + ((size_t)b * CTX + t) * DM : P.x + ((size_t)b * SEQ + (t - CTX)) * DM) : xr;
;         f32x4 v[4]; float s2 = 0.f;
; #pragma unroll
;         for (int j = 0; j < 4; ++j) { v[j] = *((const f32x4*)src + lane + 64 * j); s2 += (v[j].x * v[j].x + v[j].y * v[j].y) + (v[j].z * v[j].z + v[j].w * v[j].w); }
;         if (first) {
; #pragma unroll
;             for (int j = 0; j < 4; ++j) *((f32x4*)xr + lane + 64 * j) = v[j];
;         }
;         const float rstd = 1.0f / sqrtf(wave_sum(s2, lane) * (1.0f / DM) + RMS_EPS);
;         const float* mrow = mod + (size_t)bb * MODW;
; #pragma unroll
;         for (int j = 0; j < 4; ++j) {
;             const int c0 = 4 * (lane + 64 * j);
;             const f32x4 g = *(const f32x4*)(gain + c0), sh = *(const f32x4*)(mrow + c0), scl = *(const f32x4*)(mrow + DM + c0);
;             const f32x4 y = v[j] * rstd * g * (scl + 1.0f) + sh;
;             u32x2 w; w.x = pk2(y.x, y.y); w.y = pk2(y.z, y.w);
;             *(u32x2*)(H + (size_t)r * DM + c0) = w;
;         }
;     }
	v_mul_f32_e32 v193, v40, v179
	v_add_f32_e32 v192, 1.0, v146
	v_mul_f32_e32 v193, v162, v193
	v_fma_f32 v180, v192, v193, v130
	v_mul_f32_e32 v193, v41, v179
	v_add_f32_e32 v192, 1.0, v147
	v_mul_f32_e32 v193, v163, v193
	v_fma_f32 v181, v192, v193, v131
	v_mul_f32_e32 v193, v42, v179
	v_add_f32_e32 v192, 1.0, v148
	v_mul_f32_e32 v193, v164, v193
	v_fma_f32 v182, v192, v193, v132
	v_mul_f32_e32 v193, v43, v179
	v_add_f32_e32 v192, 1.0, v149
	v_mul_f32_e32 v193, v165, v193
	v_fma_f32 v183, v192, v193, v133
	v_cvt_pk_bf16_f32 v184, v180, v181
	v_cvt_pk_bf16_f32 v185, v182, v183
	global_store_dwordx2 v121, v[184:185], s[12:13]
	v_mul_f32_e32 v193, v44, v179
	v_add_f32_e32 v192, 1.0, v150
	v_mul_f32_e32 v193, v166, v193
	v_fma_f32 v180, v192, v193, v134
	v_mul_f32_e32 v193, v45, v179
	v_add_f32_e32 v192, 1.0, v151
	v_mul_f32_e32 v193, v167, v193
	v_fma_f32 v181, v192, v193, v135
	v_mul_f32_e32 v193, v46, v179
	v_add_f32_e32 v192, 1.0, v152
	v_mul_f32_e32 v193, v168, v193
	v_fma_f32 v182, v192, v193, v136
	v_mul_f32_e32 v193, v47, v179
	v_add_f32_e32 v192, 1.0, v153
	v_mul_f32_e32 v193, v169, v193
	v_fma_f32 v183, v192, v193, v137
	v_cvt_pk_bf16_f32 v186, v180, v181
	v_cvt_pk_bf16_f32 v187, v182, v183
	global_store_dwordx2 v121, v[186:187], s[12:13] offset:512
	v_mul_f32_e32 v193, v48, v179
	v_add_f32_e32 v192, 1.0, v154
	v_mul_f32_e32 v193, v170, v193
	v_fma_f32 v180, v192, v193, v138
	v_mul_f32_e32 v193, v49, v179
	v_add_f32_e32 v192, 1.0, v155
	v_mul_f32_e32 v193, v171, v193
	v_fma_f32 v181, v192, v193, v139
	v_mul_f32_e32 v193, v50, v179
	v_add_f32_e32 v192, 1.0, v156
	v_mul_f32_e32 v193, v172, v193
	v_fma_f32 v182, v192, v193, v140
	v_mul_f32_e32 v193, v51, v179
	v_add_f32_e32 v192, 1.0, v157
	v_mul_f32_e32 v193, v173, v193
	v_fma_f32 v183, v192, v193, v141
	v_cvt_pk_bf16_f32 v188, v180, v181
	v_cvt_pk_bf16_f32 v189, v182, v183
	global_store_dwordx2 v121, v[188:189], s[12:13] offset:1024
	v_mul_f32_e32 v193, v52, v179
	v_add_f32_e32 v192, 1.0, v158
	v_mul_f32_e32 v193, v174, v193
	v_fma_f32 v180, v192, v193, v142
	v_mul_f32_e32 v193, v53, v179
	v_add_f32_e32 v192, 1.0, v159
	v_mul_f32_e32 v193, v175, v193
	v_fma_f32 v181, v192, v193, v143
	v_mul_f32_e32 v193, v54, v179
	v_add_f32_e32 v192, 1.0, v160
	v_mul_f32_e32 v193, v176, v193
	v_fma_f32 v182, v192, v193, v144
	v_mul_f32_e32 v193, v55, v179
	v_add_f32_e32 v192, 1.0, v161
	v_mul_f32_e32 v193, v177, v193
	v_fma_f32 v183, v192, v193, v145
	v_cvt_pk_bf16_f32 v190, v180, v181
	v_cvt_pk_bf16_f32 v191, v182, v183
	global_store_dwordx2 v121, v[190:191], s[12:13] offset:1536
	s_lshr_b32 s8, s101, 8
	s_mul_i32 s8, s8, 57
	s_lshr_b32 s8, s8, 9
	s_mul_i32 s9, s8, 0x900
	s_sub_u32 s9, s101, s9
	s_lshl_b32 s12, s8, 11
	s_add_u32 s12, s12, s9
	s_sub_u32 s12, s12, 0x100
	s_lshl_b32 s8, s8, 8
	s_add_u32 s8, s8, s9
	s_cmp_lt_u32 s9, 0x100
	s_cselect_b32 s8, s8, s12
	s_cselect_b32 s12, s36, s56
	s_cselect_b32 s13, s37, s57
	s_lshl_b32 s8, s8, 12
	s_add_u32 s12, s12, s8
	s_addc_u32 s13, s13, 0
	global_store_dwordx4 v120, v[40:43], s[12:13]
	global_store_dwordx4 v120, v[44:47], s[12:13] offset:1024
	global_store_dwordx4 v120, v[48:51], s[12:13] offset:2048
	global_store_dwordx4 v120, v[52:55], s[12:13] offset:3072
	s_mul_i32 s100, s68, 3
	s_add_u32 s100, s100, s101
	s_cmp_le_u32 s100, s71
	s_cselect_b32 s100, s100, s101
	s_lshr_b32 s8, s100, 8
	s_mul_i32 s8, s8, 57
	s_lshr_b32 s8, s8, 9
	s_mul_i32 s9, s8, 0x900
	s_sub_u32 s9, s100, s9
	s_lshl_b32 s12, s8, 11
	s_add_u32 s12, s12, s9
	s_sub_u32 s12, s12, 0x100
	s_lshl_b32 s8, s8, 8
	s_add_u32 s8, s8, s9
	s_cmp_lt_u32 s9, 0x100
	s_cselect_b32 s8, s8, s12
	s_cselect_b32 s12, s48, s40
	s_cselect_b32 s13, s49, s41
	s_lshl_b32 s8, s8, 12
	s_add_u32 s12, s12, s8
	s_addc_u32 s13, s13, 0
	global_load_dwordx4 v[40:43], v120, s[12:13]
	global_load_dwordx4 v[44:47], v120, s[12:13] offset:1024
	global_load_dwordx4 v[48:51], v120, s[12:13] offset:2048
	global_load_dwordx4 v[52:55], v120, s[12:13] offset:3072
	s_add_u32 s101, s101, s68
	s_cmp_gt_u32 s101, s71
	s_cbranch_scc1 .Lnf_n1f_exit
.Lnf_n1f_loop:
	s_waitcnt vmcnt(40)
	s_add_u32 s100, s101, s68
	s_cmp_le_u32 s100, s71
	s_cselect_b32 s100, s100, s101
	s_lshr_b32 s8, s100, 8
	s_mul_i32 s8, s8, 57
	s_lshr_b32 s8, s8, 9
	s_mul_i32 s9, s8, 0x900
	s_sub_u32 s9, s100, s9
	s_cmp_lt_u32 s9, 0x100
	s_cselect_b32 s8, 16, s8
	s_mul_i32 s8, s8, 0x6000
	s_add_u32 s12, s50, s8
	s_addc_u32 s13, s51, 0
	global_load_dwordx4 v[88:91], v120, s[12:13] offset:-4096
	global_load_dwordx4 v[92:95], v120, s[12:13] offset:-3072
	global_load_dwordx4 v[96:99], v120, s[12:13] offset:-2048
	global_load_dwordx4 v[100:103], v120, s[12:13] offset:-1024
	global_load_dwordx4 v[104:107], v120, s[12:13]
	global_load_dwordx4 v[108:111], v120, s[12:13] offset:1024
	global_load_dwordx4 v[112:115], v120, s[12:13] offset:2048
	global_load_dwordx4 v[116:119], v120, s[12:13] offset:3072
	v_mul_f32_e32 v32, v1, v1
	v_mul_f32_e32 v33, v3, v3
	v_fmac_f32_e32 v32, v0, v0
	v_fmac_f32_e32 v33, v2, v2
	v_add_f32_e32 v34, v32, v33
	v_mul_f32_e32 v32, v5, v5
	v_mul_f32_e32 v33, v7, v7
	v_fmac_f32_e32 v32, v4, v4
	v_fmac_f32_e32 v33, v6, v6
	v_add_f32_e32 v32, v32, v33
	v_add_f32_e32 v34, v34, v32
	v_mul_f32_e32 v32, v9, v9
	v_mul_f32_e32 v33, v11, v11
	v_fmac_f32_e32 v32, v8, v8
	v_fmac_f32_e32 v33, v10, v10
	v_add_f32_e32 v32, v32, v33
	v_add_f32_e32 v34, v34, v32
	v_mul_f32_e32 v32, v13, v13
	v_mul_f32_e32 v33, v15, v15
	v_fmac_f32_e32 v32, v12, v12
	v_fmac_f32_e32 v33, v14, v14
	v_add_f32_e32 v32, v32, v33
	v_add_f32_e32 v34, v34, v32
	ds_bpermute_b32 v32, v122, v34
	s_waitcnt lgkmcnt(0)
	v_add_f32_e32 v34, v34, v32
	ds_bpermute_b32 v32, v123, v34
	s_waitcnt lgkmcnt(0)
; __device__ __forceinline__ unsigned pk2(float lo, float hi) { f32x2_t v = {lo, hi}; bf16x2_t b = __builtin_convertvector(v, bf16x2_t); return __builtin_bit_cast(unsigned, b); }
; __device__ __forceinline__ void phase_norm(const Params& P, int l, int which, bool first) {
;     ...
;     for (int r = gw; r < ROWS; r += NGW) {
;         const int b = r / TT, t = r - b * TT; const int bb = (t < CTX) ? 16 : b;
;         float* xr = xrow_ptr(P, r);
;         const float* src = first ? ((t < CTX) ? P.ctx + ((size_t)b * CTX + t) * DM : P.x + ((size_t)b * SEQ + (t - CTX)) * DM) : xr;
;         f32x4 v[4]; float s2 = 0.f;
; #pragma unroll
;         for (int j = 0; j < 4; ++j) { v[j] = *((const f32x4*)src + lane + 64 * j); s2 += (v[j].x * v[j].x + v[j].y * v[j].y) + (v[j].z * v[j].z + v[j].w * v[j].w); }
;         if (first) {
; #pragma unroll
;             for (int j = 0; j < 4; ++j) *((f32x4*)xr + lane + 64 * j) = v[j];
;         }
;         const float rstd = 1.0f / sqrtf(wave_sum(s2, lane) * (1.0f / DM) + RMS_EPS);
;         const float* mrow = mod + (size_t)bb * MODW;
; #pragma unroll
;         for (int j = 0; j < 4; ++j) {
;             const int c0 = 4 * (lane + 64 * j);
;             const f32x4 g = *(const f32x4*)(gain + c0), sh = *(const f32x4*)(mrow + c0), scl = *(const f32x4*)(mrow + DM + c0);
;             const f32x4 y = v[j] * rstd * g * (scl + 1.0f) + sh;
;             u32x2 w; w.x = pk2(y.x, y.y); w.y = pk2(y.z, y.w);
;             *(u32x2*)(H + (size_t)r * DM + c0) = w;
;         }
;     }
	v_add_f32_e32 v34, v34, v32
	ds_bpermute_b32 v32, v124, v34
	s_waitcnt lgkmcnt(0)
	v_add_f32_e32 v34, v34, v32
	ds_bpermute_b32 v32, v125, v34
	s_waitcnt lgkmcnt(0)
	v_add_f32_e32 v34, v34, v32
	ds_bpermute_b32 v32, v126, v34
	s_waitcnt lgkmcnt(0)
	v_add_f32_e32 v34, v34, v32
	ds_bpermute_b32 v32, v127, v34
	s_waitcnt lgkmcnt(0)
	v_add_f32_e32 v34, v34, v32
	v_fmamk_f32 v34, v34, 0x3a800000, v201
	v_cmp_gt_f32_e32 vcc, 0xf800000, v34
	v_mul_f32_e32 v32, 0x4f800000, v34
	s_nop 0
	v_cndmask_b32_e32 v34, v34, v32, vcc
	v_sqrt_f32_e32 v32, v34
	s_nop 0
	v_add_u32_e32 v35, -1, v32
	v_fma_f32 v36, -v35, v32, v34
	v_cmp_ge_f32_e64 s[38:39], 0, v36
	v_add_u32_e32 v36, 1, v32
	s_nop 0
	v_cndmask_b32_e64 v35, v32, v35, s[38:39]
	v_fma_f32 v32, -v36, v32, v34
	v_cmp_lt_f32_e64 s[38:39], 0, v32
	s_nop 1
	v_cndmask_b32_e64 v32, v35, v36, s[38:39]
	v_mul_f32_e32 v35, 0x37800000, v32
	v_cndmask_b32_e32 v32, v32, v35, vcc
	v_cmp_class_f32_e32 vcc, v34, v202
	s_nop 1
	v_cndmask_b32_e32 v34, v32, v34, vcc
	v_div_scale_f32 v32, s[38:39], v34, v34, 1.0
	v_rcp_f32_e32 v35, v32
	s_nop 0
	v_fma_f32 v36, -v32, v35, 1.0
	v_fmac_f32_e32 v35, v36, v35
	v_div_scale_f32 v36, vcc, 1.0, v34, 1.0
	v_mul_f32_e32 v37, v36, v35
	v_fma_f32 v178, -v32, v37, v36
	v_fmac_f32_e32 v37, v178, v35
	v_fma_f32 v32, -v32, v37, v36
	v_div_fmas_f32 v32, v32, v35, v37
	v_div_fixup_f32 v179, v32, v34, 1.0
	s_lshl_b32 s8, s101, 11
	s_add_u32 s12, s58, s8
	s_addc_u32 s13, s59, 0
	s_add_u32 s12, s12, 0x5500000
	s_addc_u32 s13, s13, 0
	s_waitcnt vmcnt(20)
	v_mul_f32_e32 v193, v0, v179
	v_add_f32_e32 v192, 1.0, v72
	v_mul_f32_e32 v193, v162, v193
	v_fma_f32 v180, v192, v193, v56
	v_mul_f32_e32 v193, v1, v179
	v_add_f32_e32 v192, 1.0, v73
	v_mul_f32_e32 v193, v163, v193
	v_fma_f32 v181, v192, v193, v57
	v_mul_f32_e32 v193, v2, v179
	v_add_f32_e32 v192, 1.0, v74
	v_mul_f32_e32 v193, v164, v193
	v_fma_f32 v182, v192, v193, v58
	v_mul_f32_e32 v193, v3, v179
	v_add_f32_e32 v192, 1.0, v75
	v_mul_f32_e32 v193, v165, v193
	v_fma_f32 v183, v192, v193, v59
	v_cvt_pk_bf16_f32 v184, v180, v181
	v_cvt_pk_bf16_f32 v185, v182, v183
	global_store_dwordx2 v121, v[184:185], s[12:13]
	v_mul_f32_e32 v193, v4, v179
	v_add_f32_e32 v192, 1.0, v76
	v_mul_f32_e32 v193, v166, v193
	v_fma_f32 v180, v192, v193, v60
	v_mul_f32_e32 v193, v5, v179
	v_add_f32_e32 v192, 1.0, v77
	v_mul_f32_e32 v193, v167, v193
	v_fma_f32 v181, v192, v193, v61
	v_mul_f32_e32 v193, v6, v179
	v_add_f32_e32 v192, 1.0, v78
	v_mul_f32_e32 v193, v168, v193
	v_fma_f32 v182, v192, v193, v62
	v_mul_f32_e32 v193, v7, v179
	v_add_f32_e32 v192, 1.0, v79
	v_mul_f32_e32 v193, v169, v193
	v_fma_f32 v183, v192, v193, v63
	v_cvt_pk_bf16_f32 v186, v180, v181
	v_cvt_pk_bf16_f32 v187, v182, v183
	global_store_dwordx2 v121, v[186:187], s[12:13] offset:512
	v_mul_f32_e32 v193, v8, v179
	v_add_f32_e32 v192, 1.0, v80
	v_mul_f32_e32 v193, v170, v193
	v_fma_f32 v180, v192, v193, v64
	v_mul_f32_e32 v193, v9, v179
	v_add_f32_e32 v192, 1.0, v81
	v_mul_f32_e32 v193, v171, v193
	v_fma_f32 v181, v192, v193, v65
	v_mul_f32_e32 v193, v10, v179
	v_add_f32_e32 v192, 1.0, v82
	v_mul_f32_e32 v193, v172, v193
	v_fma_f32 v182, v192, v193, v66
	v_mul_f32_e32 v193, v11, v179
	v_add_f32_e32 v192, 1.0, v83
	v_mul_f32_e32 v193, v173, v193
	v_fma_f32 v183, v192, v193, v67
	v_cvt_pk_bf16_f32 v188, v180, v181
	v_cvt_pk_bf16_f32 v189, v182, v183
	global_store_dwordx2 v121, v[188:189], s[12:13] offset:1024
	v_mul_f32_e32 v193, v12, v179
	v_add_f32_e32 v192, 1.0, v84
	v_mul_f32_e32 v193, v174, v193
	v_fma_f32 v180, v192, v193, v68
	v_mul_f32_e32 v193, v13, v179
	v_add_f32_e32 v192, 1.0, v85
	v_mul_f32_e32 v193, v175, v193
	v_fma_f32 v181, v192, v193, v69
	v_mul_f32_e32 v193, v14, v179
	v_add_f32_e32 v192, 1.0, v86
	v_mul_f32_e32 v193, v176, v193
	v_fma_f32 v182, v192, v193, v70
	v_mul_f32_e32 v193, v15, v179
	v_add_f32_e32 v192, 1.0, v87
	v_mul_f32_e32 v193, v177, v193
	v_fma_f32 v183, v192, v193, v71
	v_cvt_pk_bf16_f32 v190, v180, v181
	v_cvt_pk_bf16_f32 v191, v182, v183
	global_store_dwordx2 v121, v[190:191], s[12:13] offset:1536
	s_lshr_b32 s8, s101, 8
	s_mul_i32 s8, s8, 57
	s_lshr_b32 s8, s8, 9
	s_mul_i32 s9, s8, 0x900
	s_sub_u32 s9, s101, s9
	s_lshl_b32 s12, s8, 11
	s_add_u32 s12, s12, s9
	s_sub_u32 s12, s12, 0x100
	s_lshl_b32 s8, s8, 8
	s_add_u32 s8, s8, s9
	s_cmp_lt_u32 s9, 0x100
	s_cselect_b32 s8, s8, s12
	s_cselect_b32 s12, s36, s56
	s_cselect_b32 s13, s37, s57
	s_lshl_b32 s8, s8, 12
	s_add_u32 s12, s12, s8
	s_addc_u32 s13, s13, 0
	global_store_dwordx4 v120, v[0:3], s[12:13]
	global_store_dwordx4 v120, v[4:7], s[12:13] offset:1024
	global_store_dwordx4 v120, v[8:11], s[12:13] offset:2048
	global_store_dwordx4 v120, v[12:15], s[12:13] offset:3072
	s_mul_i32 s100, s68, 3
	s_add_u32 s100, s100, s101
	s_cmp_le_u32 s100, s71
	s_cselect_b32 s100, s100, s101
	s_lshr_b32 s8, s100, 8
	s_mul_i32 s8, s8, 57
	s_lshr_b32 s8, s8, 9
	s_mul_i32 s9, s8, 0x900
	s_sub_u32 s9, s100, s9
	s_lshl_b32 s12, s8, 11
	s_add_u32 s12, s12, s9
	s_sub_u32 s12, s12, 0x100
	s_lshl_b32 s8, s8, 8
	s_add_u32 s8, s8, s9
	s_cmp_lt_u32 s9, 0x100
	s_cselect_b32 s8, s8, s12
	s_cselect_b32 s12, s48, s40
	s_cselect_b32 s13, s49, s41
	s_lshl_b32 s8, s8, 12
	s_add_u32 s12, s12, s8
	s_addc_u32 s13, s13, 0
	global_load_dwordx4 v[0:3], v120, s[12:13]
	global_load_dwordx4 v[4:7], v120, s[12:13] offset:1024
	global_load_dwordx4 v[8:11], v120, s[12:13] offset:2048
	global_load_dwordx4 v[12:15], v120, s[12:13] offset:3072
	s_add_u32 s101, s101, s68
	s_cmp_gt_u32 s101, s71
	s_cbranch_scc1 .Lnf_n1f_exit
; __device__ __forceinline__ unsigned pk2(float lo, float hi) { f32x2_t v = {lo, hi}; bf16x2_t b = __builtin_convertvector(v, bf16x2_t); return __builtin_bit_cast(unsigned, b); }
; __device__ __forceinline__ void phase_norm(const Params& P, int l, int which, bool first) {
;     ...
;     for (int r = gw; r < ROWS; r += NGW) {
;         const int b = r / TT, t = r - b * TT; const int bb = (t < CTX) ? 16 : b;
;         float* xr = xrow_ptr(P, r);
;         const float* src = first ? ((t < CTX) ? P.ctx + ((size_t)b * CTX + t) * DM : P.x + ((size_t)b * SEQ + (t - CTX)) * DM) : xr;
;         f32x4 v[4]; float s2 = 0.f;
; #pragma unroll
;         for (int j = 0; j < 4; ++j) { v[j] = *((const f32x4*)src + lane + 64 * j); s2 += (v[j].x * v[j].x + v[j].y * v[j].y) + (v[j].z * v[j].z + v[j].w * v[j].w); }
;         if (first) {
; #pragma unroll
;             for (int j = 0; j < 4; ++j) *((f32x4*)xr + lane + 64 * j) = v[j];
;         }
;         const float rstd = 1.0f / sqrtf(wave_sum(s2, lane) * (1.0f / DM) + RMS_EPS);
;         const float* mrow = mod + (size_t)bb * MODW;
; #pragma unroll
;         for (int j = 0; j < 4; ++j) {
;             const int c0 = 4 * (lane + 64 * j);
;             const f32x4 g = *(const f32x4*)(gain + c0), sh = *(const f32x4*)(mrow + c0), scl = *(const f32x4*)(mrow + DM + c0);
;             const f32x4 y = v[j] * rstd * g * (scl + 1.0f) + sh;
;             u32x2 w; w.x = pk2(y.x, y.y); w.y = pk2(y.z, y.w);
;             *(u32x2*)(H + (size_t)r * DM + c0) = w;
;         }
;     }
	s_waitcnt vmcnt(40)
	s_add_u32 s100, s101, s68
	s_cmp_le_u32 s100, s71
	s_cselect_b32 s100, s100, s101
	s_lshr_b32 s8, s100, 8
	s_mul_i32 s8, s8, 57
	s_lshr_b32 s8, s8, 9
	s_mul_i32 s9, s8, 0x900
	s_sub_u32 s9, s100, s9
	s_cmp_lt_u32 s9, 0x100
	s_cselect_b32 s8, 16, s8
	s_mul_i32 s8, s8, 0x6000
	s_add_u32 s12, s50, s8
	s_addc_u32 s13, s51, 0
	global_load_dwordx4 v[130:133], v120, s[12:13] offset:-4096
	global_load_dwordx4 v[134:137], v120, s[12:13] offset:-3072
	global_load_dwordx4 v[138:141], v120, s[12:13] offset:-2048
	global_load_dwordx4 v[142:145], v120, s[12:13] offset:-1024
	global_load_dwordx4 v[146:149], v120, s[12:13]
	global_load_dwordx4 v[150:153], v120, s[12:13] offset:1024
	global_load_dwordx4 v[154:157], v120, s[12:13] offset:2048
	global_load_dwordx4 v[158:161], v120, s[12:13] offset:3072
	v_mul_f32_e32 v32, v17, v17
	v_mul_f32_e32 v33, v19, v19
	v_fmac_f32_e32 v32, v16, v16
	v_fmac_f32_e32 v33, v18, v18
	v_add_f32_e32 v34, v32, v33
	v_mul_f32_e32 v32, v21, v21
	v_mul_f32_e32 v33, v23, v23
	v_fmac_f32_e32 v32, v20, v20
	v_fmac_f32_e32 v33, v22, v22
	v_add_f32_e32 v32, v32, v33
	v_add_f32_e32 v34, v34, v32
	v_mul_f32_e32 v32, v25, v25
	v_mul_f32_e32 v33, v27, v27
	v_fmac_f32_e32 v32, v24, v24
	v_fmac_f32_e32 v33, v26, v26
	v_add_f32_e32 v32, v32, v33
	v_add_f32_e32 v34, v34, v32
	v_mul_f32_e32 v32, v29, v29
	v_mul_f32_e32 v33, v31, v31
	v_fmac_f32_e32 v32, v28, v28
	v_fmac_f32_e32 v33, v30, v30
	v_add_f32_e32 v32, v32, v33
	v_add_f32_e32 v34, v34, v32
	ds_bpermute_b32 v32, v122, v34
	s_waitcnt lgkmcnt(0)
	v_add_f32_e32 v34, v34, v32
	ds_bpermute_b32 v32, v123, v34
	s_waitcnt lgkmcnt(0)
	v_add_f32_e32 v34, v34, v32
	ds_bpermute_b32 v32, v124, v34
	s_waitcnt lgkmcnt(0)
	v_add_f32_e32 v34, v34, v32
	ds_bpermute_b32 v32, v125, v34
	s_waitcnt lgkmcnt(0)
	v_add_f32_e32 v34, v34, v32
	ds_bpermute_b32 v32, v126, v34
	s_waitcnt lgkmcnt(0)
	v_add_f32_e32 v34, v34, v32
	ds_bpermute_b32 v32, v127, v34
	s_waitcnt lgkmcnt(0)
	v_add_f32_e32 v34, v34, v32
	v_fmamk_f32 v34, v34, 0x3a800000, v201
	v_cmp_gt_f32_e32 vcc, 0xf800000, v34
	v_mul_f32_e32 v32, 0x4f800000, v34
	s_nop 0
	v_cndmask_b32_e32 v34, v34, v32, vcc
	v_sqrt_f32_e32 v32, v34
	s_nop 0
	v_add_u32_e32 v35, -1, v32
	v_fma_f32 v36, -v35, v32, v34
	v_cmp_ge_f32_e64 s[38:39], 0, v36
	v_add_u32_e32 v36, 1, v32
	s_nop 0
	v_cndmask_b32_e64 v35, v32, v35, s[38:39]
	v_fma_f32 v32, -v36, v32, v34
	v_cmp_lt_f32_e64 s[38:39], 0, v32
	s_nop 1
	v_cndmask_b32_e64 v32, v35, v36, s[38:39]
	v_mul_f32_e32 v35, 0x37800000, v32
	v_cndmask_b32_e32 v32, v32, v35, vcc
	v_cmp_class_f32_e32 vcc, v34, v202
	s_nop 1
	v_cndmask_b32_e32 v34, v32, v34, vcc
	v_div_scale_f32 v32, s[38:39], v34, v34, 1.0
	v_rcp_f32_e32 v35, v32
	s_nop 0
	v_fma_f32 v36, -v32, v35, 1.0
	v_fmac_f32_e32 v35, v36, v35
	v_div_scale_f32 v36, vcc, 1.0, v34, 1.0
	v_mul_f32_e32 v37, v36, v35
	v_fma_f32 v178, -v32, v37, v36
	v_fmac_f32_e32 v37, v178, v35
	v_fma_f32 v32, -v32, v37, v36
	v_div_fmas_f32 v32, v32, v35, v37
	v_div_fixup_f32 v179, v32, v34, 1.0
	s_lshl_b32 s8, s101, 11
	s_add_u32 s12, s58, s8
	s_addc_u32 s13, s59, 0
	s_add_u32 s12, s12, 0x5500000
	s_addc_u32 s13, s13, 0
	s_waitcnt vmcnt(20)
	v_mul_f32_e32 v193, v16, v179
	v_add_f32_e32 v192, 1.0, v104
	v_mul_f32_e32 v193, v162, v193
	v_fma_f32 v180, v192, v193, v88
	v_mul_f32_e32 v193, v17, v179
	v_add_f32_e32 v192, 1.0, v105
	v_mul_f32_e32 v193, v163, v193
	v_fma_f32 v181, v192, v193, v89
	v_mul_f32_e32 v193, v18, v179
	v_add_f32_e32 v192, 1.0, v106
	v_mul_f32_e32 v193, v164, v193
	v_fma_f32 v182, v192, v193, v90
	v_mul_f32_e32 v193, v19, v179
	v_add_f32_e32 v192, 1.0, v107
	v_mul_f32_e32 v193, v165, v193
	v_fma_f32 v183, v192, v193, v91
	v_cvt_pk_bf16_f32 v184, v180, v181
	v_cvt_pk_bf16_f32 v185, v182, v183
	global_store_dwordx2 v121, v[184:185], s[12:13]
	v_mul_f32_e32 v193, v20, v179
	v_add_f32_e32 v192, 1.0, v108
	v_mul_f32_e32 v193, v166, v193
	v_fma_f32 v180, v192, v193, v92
	v_mul_f32_e32 v193, v21, v179
	v_add_f32_e32 v192, 1.0, v109
	v_mul_f32_e32 v193, v167, v193
	v_fma_f32 v181, v192, v193, v93
	v_mul_f32_e32 v193, v22, v179
	v_add_f32_e32 v192, 1.0, v110
	v_mul_f32_e32 v193, v168, v193
	v_fma_f32 v182, v192, v193, v94
	v_mul_f32_e32 v193, v23, v179
	v_add_f32_e32 v192, 1.0, v111
	v_mul_f32_e32 v193, v169, v193
	v_fma_f32 v183, v192, v193, v95
	v_cvt_pk_bf16_f32 v186, v180, v181
	v_cvt_pk_bf16_f32 v187, v182, v183
	global_store_dwordx2 v121, v[186:187], s[12:13] offset:512
	v_mul_f32_e32 v193, v24, v179
	v_add_f32_e32 v192, 1.0, v112
	v_mul_f32_e32 v193, v170, v193
	v_fma_f32 v180, v192, v193, v96
	v_mul_f32_e32 v193, v25, v179
	v_add_f32_e32 v192, 1.0, v113
	v_mul_f32_e32 v193, v171, v193
	v_fma_f32 v181, v192, v193, v97
	v_mul_f32_e32 v193, v26, v179
	v_add_f32_e32 v192, 1.0, v114
	v_mul_f32_e32 v193, v172, v193
	v_fma_f32 v182, v192, v193, v98
	v_mul_f32_e32 v193, v27, v179
	v_add_f32_e32 v192, 1.0, v115
	v_mul_f32_e32 v193, v173, v193
	v_fma_f32 v183, v192, v193, v99
	v_cvt_pk_bf16_f32 v188, v180, v181
	v_cvt_pk_bf16_f32 v189, v182, v183
	global_store_dwordx2 v121, v[188:189], s[12:13] offset:1024
	v_mul_f32_e32 v193, v28, v179
	v_add_f32_e32 v192, 1.0, v116
	v_mul_f32_e32 v193, v174, v193
	v_fma_f32 v180, v192, v193, v100
	v_mul_f32_e32 v193, v29, v179
	v_add_f32_e32 v192, 1.0, v117
	v_mul_f32_e32 v193, v175, v193
	v_fma_f32 v181, v192, v193, v101
	v_mul_f32_e32 v193, v30, v179
	v_add_f32_e32 v192, 1.0, v118
	v_mul_f32_e32 v193, v176, v193
	v_fma_f32 v182, v192, v193, v102
	v_mul_f32_e32 v193, v31, v179
	v_add_f32_e32 v192, 1.0, v119
	v_mul_f32_e32 v193, v177, v193
	v_fma_f32 v183, v192, v193, v103
	v_cvt_pk_bf16_f32 v190, v180, v181
	v_cvt_pk_bf16_f32 v191, v182, v183
; __device__ __forceinline__ unsigned pk2(float lo, float hi) { f32x2_t v = {lo, hi}; bf16x2_t b = __builtin_convertvector(v, bf16x2_t); return __builtin_bit_cast(unsigned, b); }
; __device__ __forceinline__ void phase_norm(const Params& P, int l, int which, bool first) {
;     ...
;     for (int r = gw; r < ROWS; r += NGW) {
;         const int b = r / TT, t = r - b * TT; const int bb = (t < CTX) ? 16 : b;
;         float* xr = xrow_ptr(P, r);
;         const float* src = first ? ((t < CTX) ? P.ctx + ((size_t)b * CTX + t) * DM : P.x + ((size_t)b * SEQ + (t - CTX)) * DM) : xr;
;         f32x4 v[4]; float s2 = 0.f;
; #pragma unroll
;         for (int j = 0; j < 4; ++j) { v[j] = *((const f32x4*)src + lane + 64 * j); s2 += (v[j].x * v[j].x + v[j].y * v[j].y) + (v[j].z * v[j].z + v[j].w * v[j].w); }
;         if (first) {
; #pragma unroll
;             for (int j = 0; j < 4; ++j) *((f32x4*)xr + lane + 64 * j) = v[j];
;         }
;         const float rstd = 1.0f / sqrtf(wave_sum(s2, lane) * (1.0f / DM) + RMS_EPS);
;         const float* mrow = mod + (size_t)bb * MODW;
; #pragma unroll
;         for (int j = 0; j < 4; ++j) {
;             const int c0 = 4 * (lane + 64 * j);
;             const f32x4 g = *(const f32x4*)(gain + c0), sh = *(const f32x4*)(mrow + c0), scl = *(const f32x4*)(mrow + DM + c0);
;             const f32x4 y = v[j] * rstd * g * (scl + 1.0f) + sh;
;             u32x2 w; w.x = pk2(y.x, y.y); w.y = pk2(y.z, y.w);
;             *(u32x2*)(H + (size_t)r * DM + c0) = w;
;         }
;     }
	global_store_dwordx2 v121, v[190:191], s[12:13] offset:1536
	s_lshr_b32 s8, s101, 8
	s_mul_i32 s8, s8, 57
	s_lshr_b32 s8, s8, 9
	s_mul_i32 s9, s8, 0x900
	s_sub_u32 s9, s101, s9
	s_lshl_b32 s12, s8, 11
	s_add_u32 s12, s12, s9
	s_sub_u32 s12, s12, 0x100
	s_lshl_b32 s8, s8, 8
	s_add_u32 s8, s8, s9
	s_cmp_lt_u32 s9, 0x100
	s_cselect_b32 s8, s8, s12
	s_cselect_b32 s12, s36, s56
	s_cselect_b32 s13, s37, s57
	s_lshl_b32 s8, s8, 12
	s_add_u32 s12, s12, s8
	s_addc_u32 s13, s13, 0
	global_store_dwordx4 v120, v[16:19], s[12:13]
	global_store_dwordx4 v120, v[20:23], s[12:13] offset:1024
	global_store_dwordx4 v120, v[24:27], s[12:13] offset:2048
	global_store_dwordx4 v120, v[28:31], s[12:13] offset:3072
	s_mul_i32 s100, s68, 3
	s_add_u32 s100, s100, s101
	s_cmp_le_u32 s100, s71
	s_cselect_b32 s100, s100, s101
	s_lshr_b32 s8, s100, 8
	s_mul_i32 s8, s8, 57
	s_lshr_b32 s8, s8, 9
	s_mul_i32 s9, s8, 0x900
	s_sub_u32 s9, s100, s9
	s_lshl_b32 s12, s8, 11
	s_add_u32 s12, s12, s9
	s_sub_u32 s12, s12, 0x100
	s_lshl_b32 s8, s8, 8
	s_add_u32 s8, s8, s9
	s_cmp_lt_u32 s9, 0x100
	s_cselect_b32 s8, s8, s12
	s_cselect_b32 s12, s48, s40
	s_cselect_b32 s13, s49, s41
	s_lshl_b32 s8, s8, 12
	s_add_u32 s12, s12, s8
	s_addc_u32 s13, s13, 0
	global_load_dwordx4 v[16:19], v120, s[12:13]
	global_load_dwordx4 v[20:23], v120, s[12:13] offset:1024
	global_load_dwordx4 v[24:27], v120, s[12:13] offset:2048
	global_load_dwordx4 v[28:31], v120, s[12:13] offset:3072
	s_add_u32 s101, s101, s68
	s_cmp_gt_u32 s101, s71
	s_cbranch_scc1 .Lnf_n1f_exit
	s_waitcnt vmcnt(40)
	s_add_u32 s100, s101, s68
	s_cmp_le_u32 s100, s71
	s_cselect_b32 s100, s100, s101
	s_lshr_b32 s8, s100, 8
	s_mul_i32 s8, s8, 57
	s_lshr_b32 s8, s8, 9
	s_mul_i32 s9, s8, 0x900
	s_sub_u32 s9, s100, s9
	s_cmp_lt_u32 s9, 0x100
	s_cselect_b32 s8, 16, s8
	s_mul_i32 s8, s8, 0x6000
	s_add_u32 s12, s50, s8
	s_addc_u32 s13, s51, 0
	global_load_dwordx4 v[56:59], v120, s[12:13] offset:-4096
	global_load_dwordx4 v[60:63], v120, s[12:13] offset:-3072
	global_load_dwordx4 v[64:67], v120, s[12:13] offset:-2048
	global_load_dwordx4 v[68:71], v120, s[12:13] offset:-1024
	global_load_dwordx4 v[72:75], v120, s[12:13]
	global_load_dwordx4 v[76:79], v120, s[12:13] offset:1024
	global_load_dwordx4 v[80:83], v120, s[12:13] offset:2048
	global_load_dwordx4 v[84:87], v120, s[12:13] offset:3072
	v_mul_f32_e32 v32, v41, v41
	v_mul_f32_e32 v33, v43, v43
	v_fmac_f32_e32 v32, v40, v40
	v_fmac_f32_e32 v33, v42, v42
	v_add_f32_e32 v34, v32, v33
	v_mul_f32_e32 v32, v45, v45
	v_mul_f32_e32 v33, v47, v47
	v_fmac_f32_e32 v32, v44, v44
	v_fmac_f32_e32 v33, v46, v46
	v_add_f32_e32 v32, v32, v33
	v_add_f32_e32 v34, v34, v32
	v_mul_f32_e32 v32, v49, v49
	v_mul_f32_e32 v33, v51, v51
	v_fmac_f32_e32 v32, v48, v48
	v_fmac_f32_e32 v33, v50, v50
	v_add_f32_e32 v32, v32, v33
	v_add_f32_e32 v34, v34, v32
	v_mul_f32_e32 v32, v53, v53
	v_mul_f32_e32 v33, v55, v55
	v_fmac_f32_e32 v32, v52, v52
	v_fmac_f32_e32 v33, v54, v54
	v_add_f32_e32 v32, v32, v33
	v_add_f32_e32 v34, v34, v32
	ds_bpermute_b32 v32, v122, v34
	s_waitcnt lgkmcnt(0)
	v_add_f32_e32 v34, v34, v32
	ds_bpermute_b32 v32, v123, v34
	s_waitcnt lgkmcnt(0)
	v_add_f32_e32 v34, v34, v32
	ds_bpermute_b32 v32, v124, v34
	s_waitcnt lgkmcnt(0)
	v_add_f32_e32 v34, v34, v32
	ds_bpermute_b32 v32, v125, v34
	s_waitcnt lgkmcnt(0)
	v_add_f32_e32 v34, v34, v32
	ds_bpermute_b32 v32, v126, v34
	s_waitcnt lgkmcnt(0)
	v_add_f32_e32 v34, v34, v32
	ds_bpermute_b32 v32, v127, v34
	s_waitcnt lgkmcnt(0)
	v_add_f32_e32 v34, v34, v32
	v_fmamk_f32 v34, v34, 0x3a800000, v201
	v_cmp_gt_f32_e32 vcc, 0xf800000, v34
	v_mul_f32_e32 v32, 0x4f800000, v34
	s_nop 0
	v_cndmask_b32_e32 v34, v34, v32, vcc
	v_sqrt_f32_e32 v32, v34
	s_nop 0
	v_add_u32_e32 v35, -1, v32
	v_fma_f32 v36, -v35, v32, v34
	v_cmp_ge_f32_e64 s[38:39], 0, v36
	v_add_u32_e32 v36, 1, v32
	s_nop 0
	v_cndmask_b32_e64 v35, v32, v35, s[38:39]
	v_fma_f32 v32, -v36, v32, v34
	v_cmp_lt_f32_e64 s[38:39], 0, v32
	s_nop 1
	v_cndmask_b32_e64 v32, v35, v36, s[38:39]
	v_mul_f32_e32 v35, 0x37800000, v32
	v_cndmask_b32_e32 v32, v32, v35, vcc
	v_cmp_class_f32_e32 vcc, v34, v202
	s_nop 1
	v_cndmask_b32_e32 v34, v32, v34, vcc
	v_div_scale_f32 v32, s[38:39], v34, v34, 1.0
	v_rcp_f32_e32 v35, v32
	s_nop 0
	v_fma_f32 v36, -v32, v35, 1.0
	v_fmac_f32_e32 v35, v36, v35
	v_div_scale_f32 v36, vcc, 1.0, v34, 1.0
	v_mul_f32_e32 v37, v36, v35
	v_fma_f32 v178, -v32, v37, v36
	v_fmac_f32_e32 v37, v178, v35
	v_fma_f32 v32, -v32, v37, v36
	v_div_fmas_f32 v32, v32, v35, v37
	v_div_fixup_f32 v179, v32, v34, 1.0
	s_lshl_b32 s8, s101, 11
	s_add_u32 s12, s58, s8
	s_addc_u32 s13, s59, 0
	s_add_u32 s12, s12, 0x5500000
	s_addc_u32 s13, s13, 0
	s_waitcnt vmcnt(20)
; __device__ __forceinline__ unsigned pk2(float lo, float hi) { f32x2_t v = {lo, hi}; bf16x2_t b = __builtin_convertvector(v, bf16x2_t); return __builtin_bit_cast(unsigned, b); }
; __device__ __forceinline__ void phase_norm(const Params& P, int l, int which, bool first) {
;     ...
;     for (int r = gw; r < ROWS; r += NGW) {
;         const int b = r / TT, t = r - b * TT; const int bb = (t < CTX) ? 16 : b;
;         float* xr = xrow_ptr(P, r);
;         const float* src = first ? ((t < CTX) ? P.ctx + ((size_t)b * CTX + t) * DM : P.x + ((size_t)b * SEQ + (t - CTX)) * DM) : xr;
;         f32x4 v[4]; float s2 = 0.f;
; #pragma unroll
;         for (int j = 0; j < 4; ++j) { v[j] = *((const f32x4*)src + lane + 64 * j); s2 += (v[j].x * v[j].x + v[j].y * v[j].y) + (v[j].z * v[j].z + v[j].w * v[j].w); }
;         if (first) {
; #pragma unroll
;             for (int j = 0; j < 4; ++j) *((f32x4*)xr + lane + 64 * j) = v[j];
;         }
;         const float rstd = 1.0f / sqrtf(wave_sum(s2, lane) * (1.0f / DM) + RMS_EPS);
;         const float* mrow = mod + (size_t)bb * MODW;
; #pragma unroll
;         for (int j = 0; j < 4; ++j) {
;             const int c0 = 4 * (lane + 64 * j);
;             const f32x4 g = *(const f32x4*)(gain + c0), sh = *(const f32x4*)(mrow + c0), scl = *(const f32x4*)(mrow + DM + c0);
;             const f32x4 y = v[j] * rstd * g * (scl + 1.0f) + sh;
;             u32x2 w; w.x = pk2(y.x, y.y); w.y = pk2(y.z, y.w);
;             *(u32x2*)(H + (size_t)r * DM + c0) = w;
;         }
;     }
	v_mul_f32_e32 v193, v40, v179
	v_add_f32_e32 v192, 1.0, v146
	v_mul_f32_e32 v193, v162, v193
	v_fma_f32 v180, v192, v193, v130
	v_mul_f32_e32 v193, v41, v179
	v_add_f32_e32 v192, 1.0, v147
	v_mul_f32_e32 v193, v163, v193
	v_fma_f32 v181, v192, v193, v131
	v_mul_f32_e32 v193, v42, v179
	v_add_f32_e32 v192, 1.0, v148
	v_mul_f32_e32 v193, v164, v193
	v_fma_f32 v182, v192, v193, v132
	v_mul_f32_e32 v193, v43, v179
	v_add_f32_e32 v192, 1.0, v149
	v_mul_f32_e32 v193, v165, v193
	v_fma_f32 v183, v192, v193, v133
	v_cvt_pk_bf16_f32 v184, v180, v181
	v_cvt_pk_bf16_f32 v185, v182, v183
	global_store_dwordx2 v121, v[184:185], s[12:13]
	v_mul_f32_e32 v193, v44, v179
	v_add_f32_e32 v192, 1.0, v150
	v_mul_f32_e32 v193, v166, v193
	v_fma_f32 v180, v192, v193, v134
	v_mul_f32_e32 v193, v45, v179
	v_add_f32_e32 v192, 1.0, v151
	v_mul_f32_e32 v193, v167, v193
	v_fma_f32 v181, v192, v193, v135
	v_mul_f32_e32 v193, v46, v179
	v_add_f32_e32 v192, 1.0, v152
	v_mul_f32_e32 v193, v168, v193
	v_fma_f32 v182, v192, v193, v136
	v_mul_f32_e32 v193, v47, v179
	v_add_f32_e32 v192, 1.0, v153
	v_mul_f32_e32 v193, v169, v193
	v_fma_f32 v183, v192, v193, v137
	v_cvt_pk_bf16_f32 v186, v180, v181
	v_cvt_pk_bf16_f32 v187, v182, v183
	global_store_dwordx2 v121, v[186:187], s[12:13] offset:512
	v_mul_f32_e32 v193, v48, v179
	v_add_f32_e32 v192, 1.0, v154
	v_mul_f32_e32 v193, v170, v193
	v_fma_f32 v180, v192, v193, v138
	v_mul_f32_e32 v193, v49, v179
	v_add_f32_e32 v192, 1.0, v155
	v_mul_f32_e32 v193, v171, v193
	v_fma_f32 v181, v192, v193, v139
	v_mul_f32_e32 v193, v50, v179
	v_add_f32_e32 v192, 1.0, v156
	v_mul_f32_e32 v193, v172, v193
	v_fma_f32 v182, v192, v193, v140
	v_mul_f32_e32 v193, v51, v179
	v_add_f32_e32 v192, 1.0, v157
	v_mul_f32_e32 v193, v173, v193
	v_fma_f32 v183, v192, v193, v141
	v_cvt_pk_bf16_f32 v188, v180, v181
	v_cvt_pk_bf16_f32 v189, v182, v183
	global_store_dwordx2 v121, v[188:189], s[12:13] offset:1024
	v_mul_f32_e32 v193, v52, v179
	v_add_f32_e32 v192, 1.0, v158
	v_mul_f32_e32 v193, v174, v193
	v_fma_f32 v180, v192, v193, v142
	v_mul_f32_e32 v193, v53, v179
	v_add_f32_e32 v192, 1.0, v159
	v_mul_f32_e32 v193, v175, v193
	v_fma_f32 v181, v192, v193, v143
	v_mul_f32_e32 v193, v54, v179
	v_add_f32_e32 v192, 1.0, v160
	v_mul_f32_e32 v193, v176, v193
	v_fma_f32 v182, v192, v193, v144
	v_mul_f32_e32 v193, v55, v179
	v_add_f32_e32 v192, 1.0, v161
	v_mul_f32_e32 v193, v177, v193
	v_fma_f32 v183, v192, v193, v145
	v_cvt_pk_bf16_f32 v190, v180, v181
	v_cvt_pk_bf16_f32 v191, v182, v183
	global_store_dwordx2 v121, v[190:191], s[12:13] offset:1536
	s_lshr_b32 s8, s101, 8
	s_mul_i32 s8, s8, 57
	s_lshr_b32 s8, s8, 9
	s_mul_i32 s9, s8, 0x900
	s_sub_u32 s9, s101, s9
	s_lshl_b32 s12, s8, 11
	s_add_u32 s12, s12, s9
	s_sub_u32 s12, s12, 0x100
	s_lshl_b32 s8, s8, 8
	s_add_u32 s8, s8, s9
	s_cmp_lt_u32 s9, 0x100
	s_cselect_b32 s8, s8, s12
	s_cselect_b32 s12, s36, s56
	s_cselect_b32 s13, s37, s57
	s_lshl_b32 s8, s8, 12
	s_add_u32 s12, s12, s8
	s_addc_u32 s13, s13, 0
	global_store_dwordx4 v120, v[40:43], s[12:13]
	global_store_dwordx4 v120, v[44:47], s[12:13] offset:1024
	global_store_dwordx4 v120, v[48:51], s[12:13] offset:2048
	global_store_dwordx4 v120, v[52:55], s[12:13] offset:3072
	s_mul_i32 s100, s68, 3
	s_add_u32 s100, s100, s101
	s_cmp_le_u32 s100, s71
	s_cselect_b32 s100, s100, s101
	s_lshr_b32 s8, s100, 8
	s_mul_i32 s8, s8, 57
	s_lshr_b32 s8, s8, 9
	s_mul_i32 s9, s8, 0x900
	s_sub_u32 s9, s100, s9
	s_lshl_b32 s12, s8, 11
	s_add_u32 s12, s12, s9
	s_sub_u32 s12, s12, 0x100
	s_lshl_b32 s8, s8, 8
	s_add_u32 s8, s8, s9
	s_cmp_lt_u32 s9, 0x100
	s_cselect_b32 s8, s8, s12
	s_cselect_b32 s12, s48, s40
	s_cselect_b32 s13, s49, s41
	s_lshl_b32 s8, s8, 12
	s_add_u32 s12, s12, s8
	s_addc_u32 s13, s13, 0
	global_load_dwordx4 v[40:43], v120, s[12:13]
	global_load_dwordx4 v[44:47], v120, s[12:13] offset:1024
	global_load_dwordx4 v[48:51], v120, s[12:13] offset:2048
	global_load_dwordx4 v[52:55], v120, s[12:13] offset:3072
	s_add_u32 s101, s101, s68
	s_cmp_gt_u32 s101, s71
	s_cbranch_scc1 .Lnf_n1f_exit
	s_branch .Lnf_n1f_loop
